# layer-0 weight conversion segment after AB-in re-dealt over workgroups 80..255 (first idle block 20 -> 80) so the quadrant-tail workgroups do not also convert
# speedup vs baseline: 1.1430x; 1.0088x over previous
.LBB0_653:
	v_readlane_b32 s2, v246, 4
	v_readlane_b32 s4, v244, 13
	v_readlane_b32 s3, v246, 5
	v_readlane_b32 s5, v244, 14
	s_and_b64 s[2:3], s[2:3], s[4:5]
	s_andn2_b64 vcc, exec, s[2:3]
	s_cbranch_vccnz .LBB0_692
	v_mov_b32_e32 v3, v180
	v_readlane_b32 s2, v246, 0
	s_cmp_lt_i32 s2, 0x50
	s_cbranch_scc1 .LBB0_692
	v_ashrrev_i32_e32 v26, 6, v3
	s_lshl_b32 s3, s2, 3
	v_add_u32_e32 v25, s3, v26
	v_add_u32_e32 v21, 0xfffffd80, v25
	v_cmp_lt_i32_e32 vcc, -1, v21
	s_and_saveexec_b64 s[28:29], vcc
	s_cbranch_execz .LBB0_691
	v_and_b32_e32 v16, 63, v3
	s_add_u32 s30, s12, 0x3b00000
	s_movk_i32 s3, 0x800
	v_lshrrev_b32_e32 v22, 5, v16
	v_and_b32_e32 v2, 31, v3
	v_lshrrev_b32_e32 v17, 3, v16
	v_lshlrev_b32_e32 v0, 3, v16
	v_lshl_add_u32 v1, v26, 14, 0
	s_addc_u32 s31, s13, 0
	v_cmp_gt_u32_e64 s[36:37], s3, v21
	v_lshlrev_b32_e32 v4, 2, v2
	v_mul_u32_u24_e32 v20, 0x84, v22
	v_and_b32_e32 v0, 56, v0
	v_lshlrev_b32_e32 v19, 2, v17
	v_or_b32_e32 v18, 8, v17
	v_or_b32_e32 v23, 24, v17
	v_or_b32_e32 v24, 16, v17
	s_and_saveexec_b64 s[38:39], s[36:37]
	s_cbranch_execz .LBB0_663
	v_mul_u32_u24_e32 v5, 0x84, v0
	v_add_u32_e32 v11, v1, v4
	v_add3_u32 v27, v1, v5, v19
	v_mov_b32_e32 v5, v145
	v_lshlrev_b32_e32 v144, 1, v0
	v_lshl_add_u64 v[6:7], s[24:25], 0, v[4:5]
	v_lshl_add_u64 v[8:9], s[30:31], 0, v[144:145]
	v_add_u32_e32 v5, 0x3d80, v25
	v_lshl_add_u32 v28, v21, 5, v184
	s_mov_b64 s[40:41], 0
	v_lshlrev_b32_e32 v144, 2, v2
	v_lshlrev_b32_e32 v10, 1, v0
	v_add_u32_e32 v29, v11, v20
	s_branch .LBB0_659
.LBB0_658:
	s_or_b64 exec, exec, s[4:5]
	s_movk_i32 s3, 0x3abf
	v_cmp_lt_i32_e32 vcc, s3, v30
	v_add_u32_e32 v5, 0x580, v5
	s_or_b64 s[40:41], vcc, s[40:41]
	v_add_u32_e32 v28, 0xb000, v28
	s_andn2_b64 exec, exec, s[40:41]
	s_cbranch_execz .LBB0_663

.LBB0_665:
	s_or_b64 exec, exec, s[4:5]
	s_movk_i32 s2, 0x52bf
	v_cmp_lt_i32_e32 vcc, s2, v28
	v_add_u32_e32 v5, 0xb000, v5
	s_or_b64 s[52:53], vcc, s[52:53]
	v_add_u32_e32 v27, 0x580, v27
	s_andn2_b64 exec, exec, s[52:53]
	s_cbranch_execz .LBB0_674
.LBB0_666:
	v_add_u32_e32 v28, 0x4840, v27
	s_movk_i32 s2, 0x383f
	v_cmp_lt_i32_e32 vcc, s2, v28
	s_and_saveexec_b64 s[2:3], vcc
	s_xor_b64 s[54:55], exec, s[2:3]
	s_cbranch_execz .LBB0_672
	s_movk_i32 s2, 0x483f
	v_cmp_lt_u32_e32 vcc, s2, v28
	s_and_saveexec_b64 s[2:3], vcc
	s_xor_b64 s[4:5], exec, s[2:3]
	s_cbranch_execz .LBB0_669
	v_lshrrev_b32_e32 v10, 1, v27
	v_and_b32_e32 v13, 0x7c0, v10
	v_add_u32_e32 v10, 0xffffb000, v5
	v_and_b32_e32 v12, 0xfe0, v10
	v_or_b32_e32 v29, v13, v22
	v_lshlrev_b32_e32 v144, 2, v12
	v_lshl_add_u64 v[10:11], v[6:7], 0, v[144:145]
	v_lshlrev_b32_e32 v144, 14, v29
	v_lshl_add_u64 v[10:11], v[10:11], 0, v[144:145]
	v_add_co_u32_e32 v30, vcc, 0x8000, v10
	s_mov_b32 s2, 0x10000
	s_nop 0
	v_addc_co_u32_e32 v31, vcc, 0, v11, vcc
	flat_load_dword v29, v[10:11]
	flat_load_dword v32, v[30:31]
	v_add_co_u32_e32 v30, vcc, s2, v10
	v_lshlrev_b32_e32 v144, 1, v13
	s_nop 0
	v_addc_co_u32_e32 v31, vcc, 0, v11, vcc
	flat_load_dword v33, v[30:31]
	v_add_co_u32_e32 v30, vcc, s89, v10
	s_nop 1
	v_addc_co_u32_e32 v31, vcc, 0, v11, vcc
	flat_load_dword v34, v[30:31]
	v_add_co_u32_e32 v30, vcc, 0x20000, v10
	s_nop 1
	v_addc_co_u32_e32 v31, vcc, 0, v11, vcc
	flat_load_dword v35, v[30:31]
	v_add_co_u32_e32 v30, vcc, 0x28000, v10
	s_nop 1
	v_addc_co_u32_e32 v31, vcc, 0, v11, vcc
	flat_load_dword v36, v[30:31]
	v_add_co_u32_e32 v30, vcc, 0x30000, v10
	s_nop 1
	v_addc_co_u32_e32 v31, vcc, 0, v11, vcc
	flat_load_dword v37, v[30:31]
	v_add_co_u32_e32 v30, vcc, 0x38000, v10
	s_nop 1
	v_addc_co_u32_e32 v31, vcc, 0, v11, vcc
	flat_load_dword v38, v[30:31]
	v_add_co_u32_e32 v30, vcc, 0x40000, v10
	s_nop 1
	v_addc_co_u32_e32 v31, vcc, 0, v11, vcc
	flat_load_dword v39, v[30:31]
	v_add_co_u32_e32 v30, vcc, 0x48000, v10
	s_nop 1
	v_addc_co_u32_e32 v31, vcc, 0, v11, vcc
	flat_load_dword v40, v[30:31]
	v_add_co_u32_e32 v30, vcc, 0x50000, v10
	s_nop 1
	v_addc_co_u32_e32 v31, vcc, 0, v11, vcc
	flat_load_dword v41, v[30:31]
	v_add_co_u32_e32 v30, vcc, 0x58000, v10
	s_nop 1
	v_addc_co_u32_e32 v31, vcc, 0, v11, vcc
	flat_load_dword v42, v[30:31]
	v_add_co_u32_e32 v30, vcc, 0x60000, v10
	s_nop 1
	v_addc_co_u32_e32 v31, vcc, 0, v11, vcc
	flat_load_dword v43, v[30:31]
	v_add_co_u32_e32 v30, vcc, 0x68000, v10
	s_nop 1
	v_addc_co_u32_e32 v31, vcc, 0, v11, vcc
	flat_load_dword v44, v[30:31]
	v_add_co_u32_e32 v30, vcc, 0x70000, v10
	s_nop 1
	v_addc_co_u32_e32 v31, vcc, 0, v11, vcc
	flat_load_dword v45, v[30:31]
	v_add_co_u32_e32 v30, vcc, 0x78000, v10
	s_nop 1
	v_addc_co_u32_e32 v31, vcc, 0, v11, vcc
	flat_load_dword v46, v[30:31]
	v_add_co_u32_e32 v30, vcc, 0x80000, v10
	s_nop 1
	v_addc_co_u32_e32 v31, vcc, 0, v11, vcc
	flat_load_dword v47, v[30:31]
	v_add_co_u32_e32 v30, vcc, 0x88000, v10
	s_nop 1
	v_addc_co_u32_e32 v31, vcc, 0, v11, vcc
	flat_load_dword v48, v[30:31]
	v_add_co_u32_e32 v30, vcc, 0x90000, v10
	s_nop 1
	v_addc_co_u32_e32 v31, vcc, 0, v11, vcc
	flat_load_dword v49, v[30:31]
	v_add_co_u32_e32 v30, vcc, 0x98000, v10
	s_nop 1
	v_addc_co_u32_e32 v31, vcc, 0, v11, vcc
	flat_load_dword v50, v[30:31]
	v_add_co_u32_e32 v30, vcc, 0xa0000, v10
	s_nop 1
	v_addc_co_u32_e32 v31, vcc, 0, v11, vcc
	flat_load_dword v51, v[30:31]
	v_add_co_u32_e32 v30, vcc, 0xa8000, v10
	s_nop 1
	v_addc_co_u32_e32 v31, vcc, 0, v11, vcc
	flat_load_dword v52, v[30:31]
	v_add_co_u32_e32 v30, vcc, 0xb0000, v10
	s_nop 1
	v_addc_co_u32_e32 v31, vcc, 0, v11, vcc
	flat_load_dword v53, v[30:31]
	v_add_co_u32_e32 v30, vcc, 0xb8000, v10
	s_nop 1
	v_addc_co_u32_e32 v31, vcc, 0, v11, vcc
	flat_load_dword v54, v[30:31]
	v_add_co_u32_e32 v30, vcc, 0xc0000, v10
	s_nop 1
	v_addc_co_u32_e32 v31, vcc, 0, v11, vcc
	flat_load_dword v55, v[30:31]
	v_add_co_u32_e32 v30, vcc, 0xc8000, v10
	s_nop 1
	v_addc_co_u32_e32 v31, vcc, 0, v11, vcc
	flat_load_dword v56, v[30:31]
	v_add_co_u32_e32 v30, vcc, 0xd0000, v10
	s_nop 1
	v_addc_co_u32_e32 v31, vcc, 0, v11, vcc
	flat_load_dword v57, v[30:31]
	v_add_co_u32_e32 v30, vcc, 0xd8000, v10
	s_nop 1
	v_addc_co_u32_e32 v31, vcc, 0, v11, vcc
	flat_load_dword v58, v[30:31]
	v_add_co_u32_e32 v30, vcc, 0xe0000, v10
	s_nop 1
	v_addc_co_u32_e32 v31, vcc, 0, v11, vcc
	flat_load_dword v59, v[30:31]
	v_add_co_u32_e32 v30, vcc, 0xe8000, v10
	s_nop 1
	v_addc_co_u32_e32 v31, vcc, 0, v11, vcc
	flat_load_dword v60, v[30:31]
	v_add_co_u32_e32 v30, vcc, 0xf0000, v10
	s_nop 1
	v_addc_co_u32_e32 v31, vcc, 0, v11, vcc
	v_add_co_u32_e32 v10, vcc, 0xf8000, v10
	flat_load_dword v30, v[30:31]
	s_nop 0
	v_addc_co_u32_e32 v11, vcc, 0, v11, vcc
	flat_load_dword v10, v[10:11]
	v_add_u32_e32 v11, 0x400, v15
	s_waitcnt vmcnt(0) lgkmcnt(0)
	ds_write2_b32 v15, v29, v32 offset1:66
	ds_write2_b32 v15, v33, v34 offset0:132 offset1:198
	ds_write2_b32 v11, v35, v36 offset0:8 offset1:74
	ds_write2_b32 v11, v37, v38 offset0:140 offset1:206
	v_add_u32_e32 v11, 0x800, v15
	ds_write2_b32 v11, v39, v40 offset0:16 offset1:82
	ds_write2_b32 v11, v41, v42 offset0:148 offset1:214
	v_add_u32_e32 v11, 0xc00, v15
	ds_write2_b32 v11, v43, v44 offset0:24 offset1:90
	ds_write2_b32 v11, v45, v46 offset0:156 offset1:222
	v_add_u32_e32 v11, 0x1000, v15
	ds_write2_b32 v11, v47, v48 offset0:32 offset1:98
	ds_write2_b32 v11, v49, v50 offset0:164 offset1:230
	v_add_u32_e32 v11, 0x1400, v15
	ds_write2_b32 v11, v51, v52 offset0:40 offset1:106
	ds_write2_b32 v11, v53, v54 offset0:172 offset1:238
	v_add_u32_e32 v11, 0x1800, v15
	ds_write2_b32 v11, v55, v56 offset0:48 offset1:114
	ds_write2_b32 v11, v57, v58 offset0:180 offset1:246
	v_add_u32_e32 v11, 0x1c00, v15
	ds_write2_b32 v11, v59, v60 offset0:56 offset1:122
	ds_write2_b32 v11, v30, v10 offset0:188 offset1:254
	s_waitcnt lgkmcnt(0)
	ds_read_b32 v13, v26
	ds_read_b32 v29, v26 offset:132
	v_lshl_add_u64 v[10:11], v[8:9], 0, v[144:145]
	s_waitcnt lgkmcnt(1)
	v_add_u32_e32 v13, 0x8000, v13
	s_waitcnt lgkmcnt(0)
	v_add_u32_e32 v29, 0x8000, v29
	v_perm_b32 v30, v29, v13, s81
	ds_read_b32 v13, v26 offset:264
	ds_read_b32 v29, v26 offset:396
	s_waitcnt lgkmcnt(1)
	v_add_u32_e32 v13, 0x8000, v13
	s_waitcnt lgkmcnt(0)
	v_add_u32_e32 v29, 0x8000, v29
	v_perm_b32 v31, v29, v13, s81
	ds_read_b32 v13, v26 offset:528
	ds_read_b32 v29, v26 offset:660
	s_waitcnt lgkmcnt(1)
	v_add_u32_e32 v13, 0x8000, v13
	s_waitcnt lgkmcnt(0)
	v_add_u32_e32 v29, 0x8000, v29
	v_perm_b32 v32, v29, v13, s81
	ds_read_b32 v13, v26 offset:792
	ds_read_b32 v29, v26 offset:924
	s_waitcnt lgkmcnt(1)
	v_add_u32_e32 v13, 0x8000, v13
	s_waitcnt lgkmcnt(0)
	v_add_u32_e32 v29, 0x8000, v29
	v_perm_b32 v33, v29, v13, s81
	v_or_b32_e32 v13, v12, v17
	v_lshlrev_b32_e32 v144, 12, v13
	v_lshl_add_u64 v[34:35], v[10:11], 0, v[144:145]
	flat_store_dwordx4 v[34:35], v[30:33]
	ds_read_b32 v13, v26 offset:32
	ds_read_b32 v29, v26 offset:164
	s_waitcnt lgkmcnt(0)
	v_add_u32_e32 v13, 0x8000, v13
	v_add_u32_e32 v29, 0x8000, v29
	v_perm_b32 v30, v29, v13, s81
	ds_read_b32 v13, v26 offset:296
	ds_read_b32 v29, v26 offset:428
	s_waitcnt lgkmcnt(0)
	v_add_u32_e32 v13, 0x8000, v13
	v_add_u32_e32 v29, 0x8000, v29
	v_perm_b32 v31, v29, v13, s81
	ds_read_b32 v13, v26 offset:560
	ds_read_b32 v29, v26 offset:692
	s_waitcnt lgkmcnt(0)
	v_add_u32_e32 v13, 0x8000, v13
	v_add_u32_e32 v29, 0x8000, v29
	v_perm_b32 v32, v29, v13, s81
	ds_read_b32 v13, v26 offset:824
	ds_read_b32 v29, v26 offset:956
	s_waitcnt lgkmcnt(0)
	v_add_u32_e32 v13, 0x8000, v13
	v_add_u32_e32 v29, 0x8000, v29
	v_perm_b32 v33, v29, v13, s81
	v_or_b32_e32 v13, v12, v18
	v_lshlrev_b32_e32 v144, 12, v13
	v_lshl_add_u64 v[34:35], v[10:11], 0, v[144:145]
	flat_store_dwordx4 v[34:35], v[30:33]
	ds_read_b32 v13, v26 offset:64
	ds_read_b32 v29, v26 offset:196
	s_waitcnt lgkmcnt(0)
	v_add_u32_e32 v13, 0x8000, v13
	v_add_u32_e32 v29, 0x8000, v29
	v_perm_b32 v30, v29, v13, s81
	ds_read_b32 v13, v26 offset:328
	ds_read_b32 v29, v26 offset:460
	s_waitcnt lgkmcnt(0)
	v_add_u32_e32 v13, 0x8000, v13
	v_add_u32_e32 v29, 0x8000, v29
	v_perm_b32 v31, v29, v13, s81
	ds_read_b32 v13, v26 offset:592
	ds_read_b32 v29, v26 offset:724
	s_waitcnt lgkmcnt(0)
	v_add_u32_e32 v13, 0x8000, v13
	v_add_u32_e32 v29, 0x8000, v29
	v_perm_b32 v32, v29, v13, s81
	ds_read_b32 v13, v26 offset:856
	ds_read_b32 v29, v26 offset:988
	s_waitcnt lgkmcnt(0)
	v_add_u32_e32 v13, 0x8000, v13
	v_add_u32_e32 v29, 0x8000, v29
	v_perm_b32 v33, v29, v13, s81
	v_or_b32_e32 v13, v12, v24
	v_lshlrev_b32_e32 v144, 12, v13
	v_lshl_add_u64 v[34:35], v[10:11], 0, v[144:145]
	flat_store_dwordx4 v[34:35], v[30:33]
	ds_read_b32 v13, v26 offset:96
	ds_read_b32 v29, v26 offset:228
	v_or_b32_e32 v12, v12, v23
	v_lshlrev_b32_e32 v144, 12, v12
	v_lshl_add_u64 v[10:11], v[10:11], 0, v[144:145]
	s_waitcnt lgkmcnt(0)
	v_add_u32_e32 v13, 0x8000, v13
	v_add_u32_e32 v29, 0x8000, v29
	v_perm_b32 v30, v29, v13, s81
	ds_read_b32 v13, v26 offset:360
	ds_read_b32 v29, v26 offset:492
	s_waitcnt lgkmcnt(0)
	v_add_u32_e32 v13, 0x8000, v13
	v_add_u32_e32 v29, 0x8000, v29
	v_perm_b32 v31, v29, v13, s81
	ds_read_b32 v13, v26 offset:624
	ds_read_b32 v29, v26 offset:756
	s_waitcnt lgkmcnt(0)
	v_add_u32_e32 v13, 0x8000, v13
	v_add_u32_e32 v29, 0x8000, v29
	v_perm_b32 v32, v29, v13, s81
	ds_read_b32 v13, v26 offset:888
	ds_read_b32 v29, v26 offset:1020
	s_waitcnt lgkmcnt(0)
	v_add_u32_e32 v13, 0x8000, v13
	v_add_u32_e32 v29, 0x8000, v29
	v_perm_b32 v33, v29, v13, s81
	flat_store_dwordx4 v[10:11], v[30:33]
	s_waitcnt lgkmcnt(0)
.LBB0_669:
	s_or_saveexec_b64 s[4:5], s[4:5]
	s_mov_b32 s3, 0x14000
	s_xor_b64 exec, exec, s[4:5]
	s_cbranch_execz .LBB0_671
	v_add_u32_e32 v29, 0x1000, v27
	v_and_b32_e32 v144, 0xfffff800, v29
	v_and_b32_e32 v32, 0x7c0, v29
	v_add_u32_e32 v29, 0x8b800, v5
	v_lshlrev_b64 v[10:11], 13, v[144:145]
	v_and_b32_e32 v29, 0x7e0, v29
	v_lshl_add_u64 v[12:13], s[24:25], 0, v[10:11]
	v_lshlrev_b64 v[10:11], 12, v[144:145]
	v_lshlrev_b32_e32 v144, 2, v29
	v_or_b32_e32 v30, v32, v22
	v_lshl_add_u64 v[12:13], v[12:13], 0, v[144:145]
	v_lshlrev_b32_e32 v144, 2, v2
	v_lshl_add_u64 v[12:13], v[12:13], 0, v[144:145]
	v_lshlrev_b32_e32 v144, 13, v30
	v_lshl_add_u64 v[12:13], v[12:13], 0, v[144:145]
	s_movk_i32 s2, 0x4000
	v_add_co_u32_e32 v30, vcc, s2, v12
	s_mov_b32 s2, 0x8000
	s_nop 0
	v_addc_co_u32_e32 v31, vcc, 0, v13, vcc
	flat_load_dword v33, v[12:13]
	flat_load_dword v34, v[30:31]
	v_add_co_u32_e32 v30, vcc, s2, v12
	s_mov_b32 s2, 0xc000
	s_nop 0
	v_addc_co_u32_e32 v31, vcc, 0, v13, vcc
	flat_load_dword v35, v[30:31]
	v_add_co_u32_e32 v30, vcc, s2, v12
	s_mov_b32 s2, 0x10000
	s_nop 0
	v_addc_co_u32_e32 v31, vcc, 0, v13, vcc
	flat_load_dword v36, v[30:31]
	v_add_co_u32_e32 v30, vcc, s2, v12
	s_mov_b32 s2, 0x1c000
	s_nop 0
	v_addc_co_u32_e32 v31, vcc, 0, v13, vcc
	flat_load_dword v37, v[30:31]
	v_add_co_u32_e32 v30, vcc, s3, v12
	v_lshlrev_b32_e32 v144, 1, v32
	s_nop 0
	v_addc_co_u32_e32 v31, vcc, 0, v13, vcc
	flat_load_dword v38, v[30:31]
	v_add_co_u32_e32 v30, vcc, s89, v12
	v_lshl_add_u64 v[10:11], s[30:31], 0, v[10:11]
	s_nop 0
	v_addc_co_u32_e32 v31, vcc, 0, v13, vcc
	flat_load_dword v39, v[30:31]
	v_add_co_u32_e32 v30, vcc, s2, v12
	s_mov_b32 s2, 0x20000
	s_nop 0
	v_addc_co_u32_e32 v31, vcc, 0, v13, vcc
	flat_load_dword v40, v[30:31]
	v_add_co_u32_e32 v30, vcc, s2, v12
	s_mov_b32 s2, 0x24000
	s_nop 0
	v_addc_co_u32_e32 v31, vcc, 0, v13, vcc
	flat_load_dword v41, v[30:31]
	v_add_co_u32_e32 v30, vcc, s2, v12
	s_mov_b32 s2, 0x28000
	s_nop 0
	v_addc_co_u32_e32 v31, vcc, 0, v13, vcc
	flat_load_dword v42, v[30:31]
	v_add_co_u32_e32 v30, vcc, s2, v12
	s_mov_b32 s2, 0x2c000
	s_nop 0
	v_addc_co_u32_e32 v31, vcc, 0, v13, vcc
	flat_load_dword v43, v[30:31]
	v_add_co_u32_e32 v30, vcc, s2, v12
	s_mov_b32 s2, 0x30000
	s_nop 0
	v_addc_co_u32_e32 v31, vcc, 0, v13, vcc
	flat_load_dword v44, v[30:31]
	v_add_co_u32_e32 v30, vcc, s2, v12
	s_mov_b32 s2, 0x34000
	s_nop 0
	v_addc_co_u32_e32 v31, vcc, 0, v13, vcc
	flat_load_dword v45, v[30:31]
	v_add_co_u32_e32 v30, vcc, s2, v12
	s_mov_b32 s2, 0x38000
	s_nop 0
	v_addc_co_u32_e32 v31, vcc, 0, v13, vcc
	flat_load_dword v46, v[30:31]
	v_add_co_u32_e32 v30, vcc, s2, v12
	s_mov_b32 s2, 0x3c000
	s_nop 0
	v_addc_co_u32_e32 v31, vcc, 0, v13, vcc
	flat_load_dword v47, v[30:31]
	v_add_co_u32_e32 v30, vcc, s2, v12
	s_mov_b32 s2, 0x40000
	s_nop 0
	v_addc_co_u32_e32 v31, vcc, 0, v13, vcc
	flat_load_dword v48, v[30:31]
	v_add_co_u32_e32 v30, vcc, s2, v12
	s_mov_b32 s2, 0x44000
	s_nop 0
	v_addc_co_u32_e32 v31, vcc, 0, v13, vcc
	flat_load_dword v49, v[30:31]
	v_add_co_u32_e32 v30, vcc, s2, v12
	s_mov_b32 s2, 0x48000
	s_nop 0
	v_addc_co_u32_e32 v31, vcc, 0, v13, vcc
	flat_load_dword v50, v[30:31]
	v_add_co_u32_e32 v30, vcc, s2, v12
	s_mov_b32 s2, 0x4c000
	s_nop 0
	v_addc_co_u32_e32 v31, vcc, 0, v13, vcc
	flat_load_dword v51, v[30:31]
	v_add_co_u32_e32 v30, vcc, s2, v12
	s_mov_b32 s2, 0x50000
	s_nop 0
	v_addc_co_u32_e32 v31, vcc, 0, v13, vcc
	flat_load_dword v52, v[30:31]
	v_add_co_u32_e32 v30, vcc, s2, v12
	s_mov_b32 s2, 0x54000
	s_nop 0
	v_addc_co_u32_e32 v31, vcc, 0, v13, vcc
	flat_load_dword v53, v[30:31]
	v_add_co_u32_e32 v30, vcc, s2, v12
	s_mov_b32 s2, 0x58000
	s_nop 0
	v_addc_co_u32_e32 v31, vcc, 0, v13, vcc
	flat_load_dword v54, v[30:31]
	v_add_co_u32_e32 v30, vcc, s2, v12
	s_mov_b32 s2, 0x5c000
	s_nop 0
	v_addc_co_u32_e32 v31, vcc, 0, v13, vcc
	flat_load_dword v55, v[30:31]
	v_add_co_u32_e32 v30, vcc, s2, v12
	s_mov_b32 s2, 0x60000
	s_nop 0
	v_addc_co_u32_e32 v31, vcc, 0, v13, vcc
	flat_load_dword v56, v[30:31]
	v_add_co_u32_e32 v30, vcc, s2, v12
	s_mov_b32 s2, 0x64000
	s_nop 0
	v_addc_co_u32_e32 v31, vcc, 0, v13, vcc
	flat_load_dword v57, v[30:31]
	v_add_co_u32_e32 v30, vcc, s2, v12
	s_mov_b32 s2, 0x68000
	s_nop 0
	v_addc_co_u32_e32 v31, vcc, 0, v13, vcc
	flat_load_dword v58, v[30:31]
	v_add_co_u32_e32 v30, vcc, s2, v12
	s_mov_b32 s2, 0x6c000
	s_nop 0
	v_addc_co_u32_e32 v31, vcc, 0, v13, vcc
	flat_load_dword v59, v[30:31]
	v_add_co_u32_e32 v30, vcc, s2, v12
	s_mov_b32 s2, 0x70000
	s_nop 0
	v_addc_co_u32_e32 v31, vcc, 0, v13, vcc
	flat_load_dword v60, v[30:31]
	v_add_co_u32_e32 v30, vcc, s2, v12
	s_mov_b32 s2, 0x74000
	s_nop 0
	v_addc_co_u32_e32 v31, vcc, 0, v13, vcc
	flat_load_dword v61, v[30:31]
	v_add_co_u32_e32 v30, vcc, s2, v12
	s_mov_b32 s2, 0x78000
	s_nop 0
	v_addc_co_u32_e32 v31, vcc, 0, v13, vcc
	flat_load_dword v62, v[30:31]
	v_add_co_u32_e32 v30, vcc, s2, v12
	s_mov_b32 s2, 0x7c000
	s_nop 0
	v_addc_co_u32_e32 v31, vcc, 0, v13, vcc
	v_add_co_u32_e32 v12, vcc, s2, v12
	flat_load_dword v30, v[30:31]
	s_nop 0
	v_addc_co_u32_e32 v13, vcc, 0, v13, vcc
	flat_load_dword v12, v[12:13]
	v_add_u32_e32 v13, 0x400, v15
	s_waitcnt vmcnt(0) lgkmcnt(0)
	ds_write2_b32 v15, v33, v34 offset1:66
	ds_write2_b32 v15, v35, v36 offset0:132 offset1:198
	ds_write2_b32 v13, v37, v38 offset0:8 offset1:74
	ds_write2_b32 v13, v39, v40 offset0:140 offset1:206
	v_add_u32_e32 v13, 0x800, v15
	ds_write2_b32 v13, v41, v42 offset0:16 offset1:82
	ds_write2_b32 v13, v43, v44 offset0:148 offset1:214
	v_add_u32_e32 v13, 0xc00, v15
	ds_write2_b32 v13, v45, v46 offset0:24 offset1:90
	ds_write2_b32 v13, v47, v48 offset0:156 offset1:222
	v_add_u32_e32 v13, 0x1000, v15
	ds_write2_b32 v13, v49, v50 offset0:32 offset1:98
	ds_write2_b32 v13, v51, v52 offset0:164 offset1:230
	v_add_u32_e32 v13, 0x1400, v15
	ds_write2_b32 v13, v53, v54 offset0:40 offset1:106
	ds_write2_b32 v13, v55, v56 offset0:172 offset1:238
	v_add_u32_e32 v13, 0x1800, v15
	ds_write2_b32 v13, v57, v58 offset0:48 offset1:114
	ds_write2_b32 v13, v59, v60 offset0:180 offset1:246
	v_add_u32_e32 v13, 0x1c00, v15
	ds_write2_b32 v13, v61, v62 offset0:56 offset1:122
	ds_write2_b32 v13, v30, v12 offset0:188 offset1:254
	s_waitcnt lgkmcnt(0)
	ds_read_b32 v12, v26
	ds_read_b32 v13, v26 offset:132
	v_lshl_add_u64 v[10:11], v[10:11], 0, v[144:145]
	v_lshlrev_b32_e32 v144, 1, v0
	v_lshl_add_u64 v[10:11], v[10:11], 0, v[144:145]
	s_waitcnt lgkmcnt(1)
	v_add_u32_e32 v12, 0x8000, v12
	s_waitcnt lgkmcnt(0)
	v_add_u32_e32 v13, 0x8000, v13
	v_perm_b32 v30, v13, v12, s81
	ds_read_b32 v12, v26 offset:264
	ds_read_b32 v13, v26 offset:396
	s_waitcnt lgkmcnt(1)
	v_add_u32_e32 v12, 0x8000, v12
	s_waitcnt lgkmcnt(0)
	v_add_u32_e32 v13, 0x8000, v13
	v_perm_b32 v31, v13, v12, s81
	ds_read_b32 v12, v26 offset:528
	ds_read_b32 v13, v26 offset:660
	s_waitcnt lgkmcnt(1)
	v_add_u32_e32 v12, 0x8000, v12
	s_waitcnt lgkmcnt(0)
	v_add_u32_e32 v13, 0x8000, v13
	v_perm_b32 v32, v13, v12, s81
	ds_read_b32 v12, v26 offset:792
	ds_read_b32 v13, v26 offset:924
	s_waitcnt lgkmcnt(1)
	v_add_u32_e32 v12, 0x8000, v12
	s_waitcnt lgkmcnt(0)
	v_add_u32_e32 v13, 0x8000, v13
	v_perm_b32 v33, v13, v12, s81
	v_or_b32_e32 v12, v29, v17
	v_lshlrev_b32_e32 v144, 12, v12
	v_lshl_add_u64 v[12:13], v[10:11], 0, v[144:145]
	flat_store_dwordx4 v[12:13], v[30:33]
	ds_read_b32 v12, v26 offset:32
	ds_read_b32 v13, v26 offset:164
	s_waitcnt lgkmcnt(0)
	v_add_u32_e32 v12, 0x8000, v12
	v_add_u32_e32 v13, 0x8000, v13
	v_perm_b32 v30, v13, v12, s81
	ds_read_b32 v12, v26 offset:296
	ds_read_b32 v13, v26 offset:428
	s_waitcnt lgkmcnt(0)
	v_add_u32_e32 v12, 0x8000, v12
	v_add_u32_e32 v13, 0x8000, v13
	v_perm_b32 v31, v13, v12, s81
	ds_read_b32 v12, v26 offset:560
	ds_read_b32 v13, v26 offset:692
	s_waitcnt lgkmcnt(0)
	v_add_u32_e32 v12, 0x8000, v12
	v_add_u32_e32 v13, 0x8000, v13
	v_perm_b32 v32, v13, v12, s81
	ds_read_b32 v12, v26 offset:824
	ds_read_b32 v13, v26 offset:956
	s_waitcnt lgkmcnt(0)
	v_add_u32_e32 v12, 0x8000, v12
	v_add_u32_e32 v13, 0x8000, v13
	v_perm_b32 v33, v13, v12, s81
	v_or_b32_e32 v12, v29, v18
	v_lshlrev_b32_e32 v144, 12, v12
	v_lshl_add_u64 v[12:13], v[10:11], 0, v[144:145]
	flat_store_dwordx4 v[12:13], v[30:33]
	ds_read_b32 v12, v26 offset:64
	ds_read_b32 v13, v26 offset:196
	s_waitcnt lgkmcnt(0)
	v_add_u32_e32 v12, 0x8000, v12
	v_add_u32_e32 v13, 0x8000, v13
	v_perm_b32 v30, v13, v12, s81
	ds_read_b32 v12, v26 offset:328
	ds_read_b32 v13, v26 offset:460
	s_waitcnt lgkmcnt(0)
	v_add_u32_e32 v12, 0x8000, v12
	v_add_u32_e32 v13, 0x8000, v13
	v_perm_b32 v31, v13, v12, s81
	ds_read_b32 v12, v26 offset:592
	ds_read_b32 v13, v26 offset:724
	s_waitcnt lgkmcnt(0)
	v_add_u32_e32 v12, 0x8000, v12
	v_add_u32_e32 v13, 0x8000, v13
	v_perm_b32 v32, v13, v12, s81
	ds_read_b32 v12, v26 offset:856
	ds_read_b32 v13, v26 offset:988
	s_waitcnt lgkmcnt(0)
	v_add_u32_e32 v12, 0x8000, v12
	v_add_u32_e32 v13, 0x8000, v13
	v_perm_b32 v33, v13, v12, s81
	v_or_b32_e32 v12, v29, v24
	v_lshlrev_b32_e32 v144, 12, v12
	v_lshl_add_u64 v[12:13], v[10:11], 0, v[144:145]
	flat_store_dwordx4 v[12:13], v[30:33]
	ds_read_b32 v12, v26 offset:96
	ds_read_b32 v13, v26 offset:228
	s_waitcnt lgkmcnt(0)
	v_add_u32_e32 v12, 0x8000, v12
	v_add_u32_e32 v13, 0x8000, v13
	v_perm_b32 v30, v13, v12, s81
	ds_read_b32 v12, v26 offset:360
	ds_read_b32 v13, v26 offset:492
	s_waitcnt lgkmcnt(0)
	v_add_u32_e32 v12, 0x8000, v12
	v_add_u32_e32 v13, 0x8000, v13
	v_perm_b32 v31, v13, v12, s81
	ds_read_b32 v12, v26 offset:624
	ds_read_b32 v13, v26 offset:756
	s_waitcnt lgkmcnt(0)
	v_add_u32_e32 v12, 0x8000, v12
	v_add_u32_e32 v13, 0x8000, v13
	v_perm_b32 v32, v13, v12, s81
	ds_read_b32 v12, v26 offset:888
	ds_read_b32 v13, v26 offset:1020
	s_waitcnt lgkmcnt(0)
	v_add_u32_e32 v12, 0x8000, v12
	v_add_u32_e32 v13, 0x8000, v13
	v_perm_b32 v33, v13, v12, s81
	v_or_b32_e32 v12, v29, v23
	v_lshlrev_b32_e32 v144, 12, v12
	v_lshl_add_u64 v[10:11], v[10:11], 0, v[144:145]
	flat_store_dwordx4 v[10:11], v[30:33]
	s_waitcnt lgkmcnt(0)

.LBB0_674:
	s_or_b64 exec, exec, s[40:41]
	s_and_saveexec_b64 s[40:41], s[36:37]
	s_cbranch_execz .LBB0_689
	v_mul_u32_u24_e32 v5, 0x84, v0
	v_lshlrev_b32_e32 v144, 1, v0
	v_add3_u32 v13, v1, v5, v19
	v_mov_b32_e32 v5, v145
	v_lshl_add_u64 v[6:7], s[12:13], 0, v[144:145]
	s_mov_b64 s[2:3], 0x6b00000
	v_add3_u32 v12, v1, v4, v20
	v_lshl_add_u64 v[4:5], s[34:35], 0, v[4:5]
	v_lshl_add_u64 v[6:7], v[6:7], 0, s[2:3]
	v_add_u32_e32 v15, 0x6d80, v25
	s_mov_b64 s[34:35], 0
	s_branch .LBB0_677
.LBB0_676:
	s_or_b64 exec, exec, s[4:5]
	s_movk_i32 s2, 0x6abf
	v_cmp_lt_i32_e32 vcc, s2, v25
	v_add_u32_e32 v15, 0x580, v15
	s_or_b64 s[34:35], vcc, s[34:35]
	v_add_u32_e32 v14, 0xb000, v14
	s_andn2_b64 exec, exec, s[34:35]
	s_cbranch_execz .LBB0_689
.LBB0_677:
	v_add_u32_e32 v25, 0xfffff840, v15
	s_movk_i32 s2, 0x383f
	v_cmp_lt_i32_e32 vcc, s2, v25
	s_and_saveexec_b64 s[2:3], vcc
	s_xor_b64 s[36:37], exec, s[2:3]
	s_cbranch_execz .LBB0_687
	s_movk_i32 s2, 0x483f
	v_cmp_lt_u32_e32 vcc, s2, v25
	s_and_saveexec_b64 s[2:3], vcc
	s_xor_b64 s[52:53], exec, s[2:3]
	s_cbranch_execz .LBB0_684
	s_movk_i32 s2, 0x683f
	v_cmp_lt_u32_e32 vcc, s2, v25
	s_and_saveexec_b64 s[2:3], vcc
	s_xor_b64 s[4:5], exec, s[2:3]
	s_mov_b32 s3, 0x14000
	s_cbranch_execz .LBB0_681
	v_add_u32_e32 v8, 0xcb800, v14
	v_and_b32_e32 v11, 0x7c0, v15
	v_and_b32_e32 v10, 0x7e0, v8
	v_or_b32_e32 v26, v11, v22
	v_lshlrev_b32_e32 v144, 2, v10
	v_lshl_add_u64 v[8:9], v[4:5], 0, v[144:145]
	v_lshlrev_b32_e32 v144, 13, v26
	v_lshl_add_u64 v[8:9], v[8:9], 0, v[144:145]
	v_add_co_u32_e32 v26, vcc, 0x4000, v8
	flat_load_dword v28, v[8:9]
	s_nop 0
	v_addc_co_u32_e32 v27, vcc, 0, v9, vcc
	flat_load_dword v29, v[26:27]
	v_add_co_u32_e32 v26, vcc, 0x8000, v8
	s_mov_b32 s2, 0x10000
	s_nop 0
	v_addc_co_u32_e32 v27, vcc, 0, v9, vcc
	flat_load_dword v30, v[26:27]
	v_add_co_u32_e32 v26, vcc, 0xc000, v8
	v_lshlrev_b32_e32 v144, 1, v11
	s_nop 0
	v_addc_co_u32_e32 v27, vcc, 0, v9, vcc
	flat_load_dword v31, v[26:27]
	v_add_co_u32_e32 v26, vcc, s2, v8
	s_mov_b32 s2, 0x1c000
	s_nop 0
	v_addc_co_u32_e32 v27, vcc, 0, v9, vcc
	flat_load_dword v32, v[26:27]
	v_add_co_u32_e32 v26, vcc, s3, v8
	s_nop 1
	v_addc_co_u32_e32 v27, vcc, 0, v9, vcc
	flat_load_dword v33, v[26:27]
	v_add_co_u32_e32 v26, vcc, s89, v8
	s_nop 1
	v_addc_co_u32_e32 v27, vcc, 0, v9, vcc
	flat_load_dword v34, v[26:27]
	v_add_co_u32_e32 v26, vcc, s2, v8
	s_mov_b32 s2, 0x20000
	s_nop 0
	v_addc_co_u32_e32 v27, vcc, 0, v9, vcc
	flat_load_dword v35, v[26:27]
	v_add_co_u32_e32 v26, vcc, s2, v8
	s_mov_b32 s2, 0x24000
	s_nop 0
	v_addc_co_u32_e32 v27, vcc, 0, v9, vcc
	flat_load_dword v36, v[26:27]
	v_add_co_u32_e32 v26, vcc, s2, v8
	s_mov_b32 s2, 0x28000
	s_nop 0
	v_addc_co_u32_e32 v27, vcc, 0, v9, vcc
	flat_load_dword v37, v[26:27]
	v_add_co_u32_e32 v26, vcc, s2, v8
	s_mov_b32 s2, 0x2c000
	s_nop 0
	v_addc_co_u32_e32 v27, vcc, 0, v9, vcc
	flat_load_dword v38, v[26:27]
	v_add_co_u32_e32 v26, vcc, s2, v8
	s_mov_b32 s2, 0x30000
	s_nop 0
	v_addc_co_u32_e32 v27, vcc, 0, v9, vcc
	flat_load_dword v39, v[26:27]
	v_add_co_u32_e32 v26, vcc, s2, v8
	s_mov_b32 s2, 0x34000
	s_nop 0
	v_addc_co_u32_e32 v27, vcc, 0, v9, vcc
	flat_load_dword v40, v[26:27]
	v_add_co_u32_e32 v26, vcc, s2, v8
	s_mov_b32 s2, 0x38000
	s_nop 0
	v_addc_co_u32_e32 v27, vcc, 0, v9, vcc
	flat_load_dword v41, v[26:27]
	v_add_co_u32_e32 v26, vcc, s2, v8
	s_mov_b32 s2, 0x3c000
	s_nop 0
	v_addc_co_u32_e32 v27, vcc, 0, v9, vcc
	flat_load_dword v42, v[26:27]
	v_add_co_u32_e32 v26, vcc, s2, v8
	s_mov_b32 s2, 0x40000
	s_nop 0
	v_addc_co_u32_e32 v27, vcc, 0, v9, vcc
	flat_load_dword v43, v[26:27]
	v_add_co_u32_e32 v26, vcc, s2, v8
	s_mov_b32 s2, 0x44000
	s_nop 0
	v_addc_co_u32_e32 v27, vcc, 0, v9, vcc
	flat_load_dword v44, v[26:27]
	v_add_co_u32_e32 v26, vcc, s2, v8
	s_mov_b32 s2, 0x48000
	s_nop 0
	v_addc_co_u32_e32 v27, vcc, 0, v9, vcc
	flat_load_dword v45, v[26:27]
	v_add_co_u32_e32 v26, vcc, s2, v8
	s_mov_b32 s2, 0x4c000
	s_nop 0
	v_addc_co_u32_e32 v27, vcc, 0, v9, vcc
	flat_load_dword v46, v[26:27]
	v_add_co_u32_e32 v26, vcc, s2, v8
	s_mov_b32 s2, 0x50000
	s_nop 0
	v_addc_co_u32_e32 v27, vcc, 0, v9, vcc
	flat_load_dword v47, v[26:27]
	v_add_co_u32_e32 v26, vcc, s2, v8
	s_mov_b32 s2, 0x54000
	s_nop 0
	v_addc_co_u32_e32 v27, vcc, 0, v9, vcc
	flat_load_dword v48, v[26:27]
	v_add_co_u32_e32 v26, vcc, s2, v8
	s_mov_b32 s2, 0x58000
	s_nop 0
	v_addc_co_u32_e32 v27, vcc, 0, v9, vcc
	flat_load_dword v49, v[26:27]
	v_add_co_u32_e32 v26, vcc, s2, v8
	s_mov_b32 s2, 0x5c000
	s_nop 0
	v_addc_co_u32_e32 v27, vcc, 0, v9, vcc
	flat_load_dword v50, v[26:27]
	v_add_co_u32_e32 v26, vcc, s2, v8
	s_mov_b32 s2, 0x60000
	s_nop 0
	v_addc_co_u32_e32 v27, vcc, 0, v9, vcc
	flat_load_dword v51, v[26:27]
	v_add_co_u32_e32 v26, vcc, s2, v8
	s_mov_b32 s2, 0x64000
	s_nop 0
	v_addc_co_u32_e32 v27, vcc, 0, v9, vcc
	flat_load_dword v52, v[26:27]
	v_add_co_u32_e32 v26, vcc, s2, v8
	s_mov_b32 s2, 0x68000
	s_nop 0
	v_addc_co_u32_e32 v27, vcc, 0, v9, vcc
	flat_load_dword v53, v[26:27]
	v_add_co_u32_e32 v26, vcc, s2, v8
	s_mov_b32 s2, 0x6c000
	s_nop 0
	v_addc_co_u32_e32 v27, vcc, 0, v9, vcc
	flat_load_dword v54, v[26:27]
	v_add_co_u32_e32 v26, vcc, s2, v8
	s_mov_b32 s2, 0x70000
	s_nop 0
	v_addc_co_u32_e32 v27, vcc, 0, v9, vcc
	flat_load_dword v55, v[26:27]
	v_add_co_u32_e32 v26, vcc, s2, v8
	s_mov_b32 s2, 0x74000
	s_nop 0
	v_addc_co_u32_e32 v27, vcc, 0, v9, vcc
	flat_load_dword v56, v[26:27]
	v_add_co_u32_e32 v26, vcc, s2, v8
	s_mov_b32 s2, 0x78000
	s_nop 0
	v_addc_co_u32_e32 v27, vcc, 0, v9, vcc
	flat_load_dword v57, v[26:27]
	v_add_co_u32_e32 v26, vcc, s2, v8
	s_mov_b32 s2, 0x7c000
	s_nop 0
	v_addc_co_u32_e32 v27, vcc, 0, v9, vcc
	v_add_co_u32_e32 v8, vcc, s2, v8
	flat_load_dword v26, v[26:27]
	s_nop 0
	v_addc_co_u32_e32 v9, vcc, 0, v9, vcc
	flat_load_dword v8, v[8:9]
	v_add_u32_e32 v9, 0x400, v12
	s_waitcnt vmcnt(0) lgkmcnt(0)
	ds_write2_b32 v12, v28, v29 offset1:66
	ds_write2_b32 v12, v30, v31 offset0:132 offset1:198
	ds_write2_b32 v9, v32, v33 offset0:8 offset1:74
	ds_write2_b32 v9, v34, v35 offset0:140 offset1:206
	v_add_u32_e32 v9, 0x800, v12
	ds_write2_b32 v9, v36, v37 offset0:16 offset1:82
	ds_write2_b32 v9, v38, v39 offset0:148 offset1:214
	v_add_u32_e32 v9, 0xc00, v12
	ds_write2_b32 v9, v40, v41 offset0:24 offset1:90
	ds_write2_b32 v9, v42, v43 offset0:156 offset1:222
	v_add_u32_e32 v9, 0x1000, v12
	ds_write2_b32 v9, v44, v45 offset0:32 offset1:98
	ds_write2_b32 v9, v46, v47 offset0:164 offset1:230
	v_add_u32_e32 v9, 0x1400, v12
	ds_write2_b32 v9, v48, v49 offset0:40 offset1:106
	ds_write2_b32 v9, v50, v51 offset0:172 offset1:238
	v_add_u32_e32 v9, 0x1800, v12
	ds_write2_b32 v9, v52, v53 offset0:48 offset1:114
	ds_write2_b32 v9, v54, v55 offset0:180 offset1:246
	v_add_u32_e32 v9, 0x1c00, v12
	ds_write2_b32 v9, v56, v57 offset0:56 offset1:122
	ds_write2_b32 v9, v26, v8 offset0:188 offset1:254
	s_waitcnt lgkmcnt(0)
	ds_read_b32 v11, v13
	ds_read_b32 v26, v13 offset:132
	v_lshl_add_u64 v[8:9], v[6:7], 0, v[144:145]
	s_waitcnt lgkmcnt(1)
	v_add_u32_e32 v11, 0x8000, v11
	s_waitcnt lgkmcnt(0)
	v_add_u32_e32 v26, 0x8000, v26
	v_perm_b32 v26, v26, v11, s81
	ds_read_b32 v11, v13 offset:264
	ds_read_b32 v27, v13 offset:396
	s_waitcnt lgkmcnt(1)
	v_add_u32_e32 v11, 0x8000, v11
	s_waitcnt lgkmcnt(0)
	v_add_u32_e32 v27, 0x8000, v27
	v_perm_b32 v27, v27, v11, s81
	ds_read_b32 v11, v13 offset:528
	ds_read_b32 v28, v13 offset:660
	s_waitcnt lgkmcnt(1)
	v_add_u32_e32 v11, 0x8000, v11
	s_waitcnt lgkmcnt(0)
	v_add_u32_e32 v28, 0x8000, v28
	v_perm_b32 v28, v28, v11, s81
	ds_read_b32 v11, v13 offset:792
	ds_read_b32 v29, v13 offset:924
	s_waitcnt lgkmcnt(1)
	v_add_u32_e32 v11, 0x8000, v11
	s_waitcnt lgkmcnt(0)
	v_add_u32_e32 v29, 0x8000, v29
	v_perm_b32 v29, v29, v11, s81
	v_or_b32_e32 v11, v10, v17
	v_lshlrev_b32_e32 v144, 12, v11
	v_lshl_add_u64 v[30:31], v[8:9], 0, v[144:145]
	flat_store_dwordx4 v[30:31], v[26:29]
	ds_read_b32 v11, v13 offset:32
	ds_read_b32 v26, v13 offset:164
	s_waitcnt lgkmcnt(0)
	v_add_u32_e32 v11, 0x8000, v11
	v_add_u32_e32 v26, 0x8000, v26
	v_perm_b32 v26, v26, v11, s81
	ds_read_b32 v11, v13 offset:296
	ds_read_b32 v27, v13 offset:428
	s_waitcnt lgkmcnt(0)
	v_add_u32_e32 v11, 0x8000, v11
	v_add_u32_e32 v27, 0x8000, v27
	v_perm_b32 v27, v27, v11, s81
	ds_read_b32 v11, v13 offset:560
	ds_read_b32 v28, v13 offset:692
	s_waitcnt lgkmcnt(0)
	v_add_u32_e32 v11, 0x8000, v11
	v_add_u32_e32 v28, 0x8000, v28
	v_perm_b32 v28, v28, v11, s81
	ds_read_b32 v11, v13 offset:824
	ds_read_b32 v29, v13 offset:956
	s_waitcnt lgkmcnt(0)
	v_add_u32_e32 v11, 0x8000, v11
	v_add_u32_e32 v29, 0x8000, v29
	v_perm_b32 v29, v29, v11, s81
	v_or_b32_e32 v11, v10, v18
	v_lshlrev_b32_e32 v144, 12, v11
	v_lshl_add_u64 v[30:31], v[8:9], 0, v[144:145]
	flat_store_dwordx4 v[30:31], v[26:29]
	ds_read_b32 v11, v13 offset:64
	ds_read_b32 v26, v13 offset:196
	s_waitcnt lgkmcnt(0)
	v_add_u32_e32 v11, 0x8000, v11
	v_add_u32_e32 v26, 0x8000, v26
	v_perm_b32 v26, v26, v11, s81
	ds_read_b32 v11, v13 offset:328
	ds_read_b32 v27, v13 offset:460
	s_waitcnt lgkmcnt(0)
	v_add_u32_e32 v11, 0x8000, v11
	v_add_u32_e32 v27, 0x8000, v27
	v_perm_b32 v27, v27, v11, s81
	ds_read_b32 v11, v13 offset:592
	ds_read_b32 v28, v13 offset:724
	s_waitcnt lgkmcnt(0)
	v_add_u32_e32 v11, 0x8000, v11
	v_add_u32_e32 v28, 0x8000, v28
	v_perm_b32 v28, v28, v11, s81
	ds_read_b32 v11, v13 offset:856
	ds_read_b32 v29, v13 offset:988
	s_waitcnt lgkmcnt(0)
	v_add_u32_e32 v11, 0x8000, v11
	v_add_u32_e32 v29, 0x8000, v29
	v_perm_b32 v29, v29, v11, s81
	v_or_b32_e32 v11, v10, v24
	v_lshlrev_b32_e32 v144, 12, v11
	v_lshl_add_u64 v[30:31], v[8:9], 0, v[144:145]
	flat_store_dwordx4 v[30:31], v[26:29]
	ds_read_b32 v11, v13 offset:96
	ds_read_b32 v26, v13 offset:228
	v_or_b32_e32 v10, v10, v23
	v_lshlrev_b32_e32 v144, 12, v10
	v_lshl_add_u64 v[8:9], v[8:9], 0, v[144:145]
	s_waitcnt lgkmcnt(0)
	v_add_u32_e32 v11, 0x8000, v11
	v_add_u32_e32 v26, 0x8000, v26
	v_perm_b32 v26, v26, v11, s81
	ds_read_b32 v11, v13 offset:360
	ds_read_b32 v27, v13 offset:492
	s_waitcnt lgkmcnt(0)
	v_add_u32_e32 v11, 0x8000, v11
	v_add_u32_e32 v27, 0x8000, v27
	v_perm_b32 v27, v27, v11, s81
	ds_read_b32 v11, v13 offset:624
	ds_read_b32 v28, v13 offset:756
	s_waitcnt lgkmcnt(0)
	v_add_u32_e32 v11, 0x8000, v11
	v_add_u32_e32 v28, 0x8000, v28
	v_perm_b32 v28, v28, v11, s81
	ds_read_b32 v11, v13 offset:888
	ds_read_b32 v29, v13 offset:1020
	s_waitcnt lgkmcnt(0)
	v_add_u32_e32 v11, 0x8000, v11
	v_add_u32_e32 v29, 0x8000, v29
	v_perm_b32 v29, v29, v11, s81
	flat_store_dwordx4 v[8:9], v[26:29]
	s_waitcnt lgkmcnt(0)
.LBB0_681:
	s_andn2_saveexec_b64 s[4:5], s[4:5]
	s_cbranch_execz .LBB0_683
	v_add_u32_e32 v26, 0xffffb000, v15
	v_lshrrev_b32_e32 v144, 12, v26
	v_lshrrev_b32_e32 v26, 1, v26
	v_and_b32_e32 v27, 0x7c0, v26
	v_add_u32_e32 v26, 0x3b000, v14
	v_lshlrev_b64 v[8:9], 25, v[144:145]
	v_and_b32_e32 v26, 0xfe0, v26
	v_lshl_add_u64 v[10:11], s[64:65], 0, v[8:9]
	v_lshlrev_b64 v[8:9], 24, v[144:145]
	v_lshlrev_b32_e32 v144, 2, v26
	v_or_b32_e32 v28, v27, v22
	v_lshl_add_u64 v[10:11], v[10:11], 0, v[144:145]
	v_lshlrev_b32_e32 v144, 2, v2
	v_lshl_add_u64 v[10:11], v[10:11], 0, v[144:145]
	v_lshlrev_b32_e32 v144, 14, v28
	v_lshl_add_u64 v[10:11], v[10:11], 0, v[144:145]
	s_mov_b32 s2, 0x8000
	v_add_co_u32_e32 v28, vcc, s2, v10
	s_mov_b32 s2, 0x10000
	s_nop 0
	v_addc_co_u32_e32 v29, vcc, 0, v11, vcc
	flat_load_dword v30, v[10:11]
	flat_load_dword v31, v[28:29]
	v_add_co_u32_e32 v28, vcc, s2, v10
	s_mov_b32 s2, 0x20000
	s_nop 0
	v_addc_co_u32_e32 v29, vcc, 0, v11, vcc
	flat_load_dword v32, v[28:29]
	v_add_co_u32_e32 v28, vcc, s89, v10
	v_lshl_add_u64 v[8:9], s[38:39], 0, v[8:9]
	s_nop 0
	v_addc_co_u32_e32 v29, vcc, 0, v11, vcc
	flat_load_dword v33, v[28:29]
	v_add_co_u32_e32 v28, vcc, s2, v10
	s_mov_b32 s2, 0x28000
	s_nop 0
	v_addc_co_u32_e32 v29, vcc, 0, v11, vcc
	flat_load_dword v34, v[28:29]
	v_add_co_u32_e32 v28, vcc, s2, v10
	s_mov_b32 s2, 0x30000
	s_nop 0
	v_addc_co_u32_e32 v29, vcc, 0, v11, vcc
	flat_load_dword v35, v[28:29]
	v_add_co_u32_e32 v28, vcc, s2, v10
	s_mov_b32 s2, 0x38000
	s_nop 0
	v_addc_co_u32_e32 v29, vcc, 0, v11, vcc
	flat_load_dword v36, v[28:29]
	v_add_co_u32_e32 v28, vcc, s2, v10
	s_mov_b32 s2, 0x40000
	s_nop 0
	v_addc_co_u32_e32 v29, vcc, 0, v11, vcc
	flat_load_dword v37, v[28:29]
	v_add_co_u32_e32 v28, vcc, s2, v10
	s_mov_b32 s2, 0x48000
	s_nop 0
	v_addc_co_u32_e32 v29, vcc, 0, v11, vcc
	flat_load_dword v38, v[28:29]
	v_add_co_u32_e32 v28, vcc, s2, v10
	s_mov_b32 s2, 0x50000
	s_nop 0
	v_addc_co_u32_e32 v29, vcc, 0, v11, vcc
	flat_load_dword v39, v[28:29]
	v_add_co_u32_e32 v28, vcc, s2, v10
	s_mov_b32 s2, 0x58000
	s_nop 0
	v_addc_co_u32_e32 v29, vcc, 0, v11, vcc
	flat_load_dword v40, v[28:29]
	v_add_co_u32_e32 v28, vcc, s2, v10
	s_mov_b32 s2, 0x60000
	s_nop 0
	v_addc_co_u32_e32 v29, vcc, 0, v11, vcc
	flat_load_dword v41, v[28:29]
	v_add_co_u32_e32 v28, vcc, s2, v10
	s_mov_b32 s2, 0x68000
	s_nop 0
	v_addc_co_u32_e32 v29, vcc, 0, v11, vcc
	flat_load_dword v42, v[28:29]
	v_add_co_u32_e32 v28, vcc, s2, v10
	s_mov_b32 s2, 0x70000
	s_nop 0
	v_addc_co_u32_e32 v29, vcc, 0, v11, vcc
	flat_load_dword v43, v[28:29]
	v_add_co_u32_e32 v28, vcc, s2, v10
	s_mov_b32 s2, 0x78000
	s_nop 0
	v_addc_co_u32_e32 v29, vcc, 0, v11, vcc
	flat_load_dword v44, v[28:29]
	v_add_co_u32_e32 v28, vcc, s2, v10
	s_mov_b32 s2, 0x80000
	s_nop 0
	v_addc_co_u32_e32 v29, vcc, 0, v11, vcc
	flat_load_dword v45, v[28:29]
	v_add_co_u32_e32 v28, vcc, s2, v10
	s_mov_b32 s2, 0x88000
	s_nop 0
	v_addc_co_u32_e32 v29, vcc, 0, v11, vcc
	flat_load_dword v46, v[28:29]
	v_add_co_u32_e32 v28, vcc, s2, v10
	s_mov_b32 s2, 0x90000
	s_nop 0
	v_addc_co_u32_e32 v29, vcc, 0, v11, vcc
	flat_load_dword v47, v[28:29]
	v_add_co_u32_e32 v28, vcc, s2, v10
	s_mov_b32 s2, 0x98000
	s_nop 0
	v_addc_co_u32_e32 v29, vcc, 0, v11, vcc
	flat_load_dword v48, v[28:29]
	v_add_co_u32_e32 v28, vcc, s2, v10
	s_mov_b32 s2, 0xa0000
	s_nop 0
	v_addc_co_u32_e32 v29, vcc, 0, v11, vcc
	flat_load_dword v49, v[28:29]
	v_add_co_u32_e32 v28, vcc, s2, v10
	s_mov_b32 s2, 0xa8000
	s_nop 0
	v_addc_co_u32_e32 v29, vcc, 0, v11, vcc
	flat_load_dword v50, v[28:29]
	v_add_co_u32_e32 v28, vcc, s2, v10
	s_mov_b32 s2, 0xb0000
	s_nop 0
	v_addc_co_u32_e32 v29, vcc, 0, v11, vcc
	flat_load_dword v51, v[28:29]
	v_add_co_u32_e32 v28, vcc, s2, v10
	s_mov_b32 s2, 0xb8000
	s_nop 0
	v_addc_co_u32_e32 v29, vcc, 0, v11, vcc
	flat_load_dword v52, v[28:29]
	v_add_co_u32_e32 v28, vcc, s2, v10
	s_mov_b32 s2, 0xc0000
	s_nop 0
	v_addc_co_u32_e32 v29, vcc, 0, v11, vcc
	flat_load_dword v53, v[28:29]
	v_add_co_u32_e32 v28, vcc, s2, v10
	s_mov_b32 s2, 0xc8000
	s_nop 0
	v_addc_co_u32_e32 v29, vcc, 0, v11, vcc
	flat_load_dword v54, v[28:29]
	v_add_co_u32_e32 v28, vcc, s2, v10
	s_mov_b32 s2, 0xd0000
	s_nop 0
	v_addc_co_u32_e32 v29, vcc, 0, v11, vcc
	flat_load_dword v55, v[28:29]
	v_add_co_u32_e32 v28, vcc, s2, v10
	s_mov_b32 s2, 0xd8000
	s_nop 0
	v_addc_co_u32_e32 v29, vcc, 0, v11, vcc
	flat_load_dword v56, v[28:29]
	v_add_co_u32_e32 v28, vcc, s2, v10
	s_mov_b32 s2, 0xe0000
	s_nop 0
	v_addc_co_u32_e32 v29, vcc, 0, v11, vcc
	flat_load_dword v57, v[28:29]
	v_add_co_u32_e32 v28, vcc, s2, v10
	s_mov_b32 s2, 0xe8000
	s_nop 0
	v_addc_co_u32_e32 v29, vcc, 0, v11, vcc
	flat_load_dword v58, v[28:29]
	v_add_co_u32_e32 v28, vcc, s2, v10
	s_mov_b32 s2, 0xf0000
	s_nop 0
	v_addc_co_u32_e32 v29, vcc, 0, v11, vcc
	flat_load_dword v59, v[28:29]
	v_add_co_u32_e32 v28, vcc, s2, v10
	s_mov_b32 s2, 0xf8000
	s_nop 0
	v_addc_co_u32_e32 v29, vcc, 0, v11, vcc
	v_add_co_u32_e32 v10, vcc, s2, v10
	flat_load_dword v28, v[28:29]
	s_nop 0
	v_addc_co_u32_e32 v11, vcc, 0, v11, vcc
	flat_load_dword v10, v[10:11]
	v_add_u32_e32 v11, 0x400, v12
	s_waitcnt vmcnt(0) lgkmcnt(0)
	ds_write2_b32 v12, v30, v31 offset1:66
	ds_write2_b32 v12, v32, v33 offset0:132 offset1:198
	ds_write2_b32 v11, v34, v35 offset0:8 offset1:74
	ds_write2_b32 v11, v36, v37 offset0:140 offset1:206
	v_add_u32_e32 v11, 0x800, v12
	ds_write2_b32 v11, v38, v39 offset0:16 offset1:82
	ds_write2_b32 v11, v40, v41 offset0:148 offset1:214
	v_add_u32_e32 v11, 0xc00, v12
	ds_write2_b32 v11, v42, v43 offset0:24 offset1:90
	ds_write2_b32 v11, v44, v45 offset0:156 offset1:222
	v_add_u32_e32 v11, 0x1000, v12
	ds_write2_b32 v11, v46, v47 offset0:32 offset1:98
	ds_write2_b32 v11, v48, v49 offset0:164 offset1:230
	v_add_u32_e32 v11, 0x1400, v12
	ds_write2_b32 v11, v50, v51 offset0:40 offset1:106
	ds_write2_b32 v11, v52, v53 offset0:172 offset1:238
	v_add_u32_e32 v11, 0x1800, v12
	ds_write2_b32 v11, v54, v55 offset0:48 offset1:114
	ds_write2_b32 v11, v56, v57 offset0:180 offset1:246
	v_add_u32_e32 v11, 0x1c00, v12
	ds_write2_b32 v11, v58, v59 offset0:56 offset1:122
	ds_write2_b32 v11, v28, v10 offset0:188 offset1:254
	s_waitcnt lgkmcnt(0)
	ds_read_b32 v10, v13
	ds_read_b32 v11, v13 offset:132
	v_lshlrev_b32_e32 v144, 1, v27
	v_lshl_add_u64 v[8:9], v[8:9], 0, v[144:145]
	v_lshlrev_b32_e32 v144, 1, v0
	s_waitcnt lgkmcnt(1)
	v_add_u32_e32 v10, 0x8000, v10
	s_waitcnt lgkmcnt(0)
	v_add_u32_e32 v11, 0x8000, v11
	v_perm_b32 v28, v11, v10, s81
	ds_read_b32 v10, v13 offset:264
	ds_read_b32 v11, v13 offset:396
	v_lshl_add_u64 v[8:9], v[8:9], 0, v[144:145]
	s_waitcnt lgkmcnt(1)
	v_add_u32_e32 v10, 0x8000, v10
	s_waitcnt lgkmcnt(0)
	v_add_u32_e32 v11, 0x8000, v11
	v_perm_b32 v29, v11, v10, s81
	ds_read_b32 v10, v13 offset:528
	ds_read_b32 v11, v13 offset:660
	s_waitcnt lgkmcnt(1)
	v_add_u32_e32 v10, 0x8000, v10
	s_waitcnt lgkmcnt(0)
	v_add_u32_e32 v11, 0x8000, v11
	v_perm_b32 v30, v11, v10, s81
	ds_read_b32 v10, v13 offset:792
	ds_read_b32 v11, v13 offset:924
	s_waitcnt lgkmcnt(1)
	v_add_u32_e32 v10, 0x8000, v10
	s_waitcnt lgkmcnt(0)
	v_add_u32_e32 v11, 0x8000, v11
	v_perm_b32 v31, v11, v10, s81
	v_or_b32_e32 v10, v26, v17
	v_lshlrev_b32_e32 v144, 12, v10
	v_lshl_add_u64 v[10:11], v[8:9], 0, v[144:145]
	flat_store_dwordx4 v[10:11], v[28:31]
	ds_read_b32 v10, v13 offset:32
	ds_read_b32 v11, v13 offset:164
	s_waitcnt lgkmcnt(0)
	v_add_u32_e32 v10, 0x8000, v10
	v_add_u32_e32 v11, 0x8000, v11
	v_perm_b32 v28, v11, v10, s81
	ds_read_b32 v10, v13 offset:296
	ds_read_b32 v11, v13 offset:428
	s_waitcnt lgkmcnt(0)
	v_add_u32_e32 v10, 0x8000, v10
	v_add_u32_e32 v11, 0x8000, v11
	v_perm_b32 v29, v11, v10, s81
	ds_read_b32 v10, v13 offset:560
	ds_read_b32 v11, v13 offset:692
	s_waitcnt lgkmcnt(0)
	v_add_u32_e32 v10, 0x8000, v10
	v_add_u32_e32 v11, 0x8000, v11
	v_perm_b32 v30, v11, v10, s81
	ds_read_b32 v10, v13 offset:824
	ds_read_b32 v11, v13 offset:956
	s_waitcnt lgkmcnt(0)
	v_add_u32_e32 v10, 0x8000, v10
	v_add_u32_e32 v11, 0x8000, v11
	v_perm_b32 v31, v11, v10, s81
	v_or_b32_e32 v10, v26, v18
	v_lshlrev_b32_e32 v144, 12, v10
	v_lshl_add_u64 v[10:11], v[8:9], 0, v[144:145]
	flat_store_dwordx4 v[10:11], v[28:31]
	ds_read_b32 v10, v13 offset:64
	ds_read_b32 v11, v13 offset:196
	s_waitcnt lgkmcnt(0)
	v_add_u32_e32 v10, 0x8000, v10
	v_add_u32_e32 v11, 0x8000, v11
	v_perm_b32 v28, v11, v10, s81
	ds_read_b32 v10, v13 offset:328
	ds_read_b32 v11, v13 offset:460
	s_waitcnt lgkmcnt(0)
	v_add_u32_e32 v10, 0x8000, v10
	v_add_u32_e32 v11, 0x8000, v11
	v_perm_b32 v29, v11, v10, s81
	ds_read_b32 v10, v13 offset:592
	ds_read_b32 v11, v13 offset:724
	s_waitcnt lgkmcnt(0)
	v_add_u32_e32 v10, 0x8000, v10
	v_add_u32_e32 v11, 0x8000, v11
	v_perm_b32 v30, v11, v10, s81
	ds_read_b32 v10, v13 offset:856
	ds_read_b32 v11, v13 offset:988
	s_waitcnt lgkmcnt(0)
	v_add_u32_e32 v10, 0x8000, v10
	v_add_u32_e32 v11, 0x8000, v11
	v_perm_b32 v31, v11, v10, s81
	v_or_b32_e32 v10, v26, v24
	v_lshlrev_b32_e32 v144, 12, v10
	v_lshl_add_u64 v[10:11], v[8:9], 0, v[144:145]
	flat_store_dwordx4 v[10:11], v[28:31]
	ds_read_b32 v10, v13 offset:96
	ds_read_b32 v11, v13 offset:228
	s_waitcnt lgkmcnt(0)
	v_add_u32_e32 v10, 0x8000, v10
	v_add_u32_e32 v11, 0x8000, v11
	v_perm_b32 v28, v11, v10, s81
	ds_read_b32 v10, v13 offset:360
	ds_read_b32 v11, v13 offset:492
	s_waitcnt lgkmcnt(0)
	v_add_u32_e32 v10, 0x8000, v10
	v_add_u32_e32 v11, 0x8000, v11
	v_perm_b32 v29, v11, v10, s81
	ds_read_b32 v10, v13 offset:624
	ds_read_b32 v11, v13 offset:756
	s_waitcnt lgkmcnt(0)
	v_add_u32_e32 v10, 0x8000, v10
	v_add_u32_e32 v11, 0x8000, v11
	v_perm_b32 v30, v11, v10, s81
	ds_read_b32 v10, v13 offset:888
	ds_read_b32 v11, v13 offset:1020
	s_waitcnt lgkmcnt(0)
	v_add_u32_e32 v10, 0x8000, v10
	v_add_u32_e32 v11, 0x8000, v11
	v_perm_b32 v31, v11, v10, s81
	v_or_b32_e32 v10, v26, v23
	v_lshlrev_b32_e32 v144, 12, v10
	v_lshl_add_u64 v[8:9], v[8:9], 0, v[144:145]
	flat_store_dwordx4 v[8:9], v[28:31]
	s_waitcnt lgkmcnt(0)

.LBB0_684:
	s_or_saveexec_b64 s[4:5], s[52:53]
	s_mov_b32 s3, 0x14000
	s_xor_b64 exec, exec, s[4:5]
	s_cbranch_execz .LBB0_686
	v_add_u32_e32 v26, 0xffffc000, v15
	v_and_b32_e32 v144, 0xfffff800, v26
	v_and_b32_e32 v27, 0x7c0, v26
	v_add_u32_e32 v26, 0xcb800, v14
	v_lshlrev_b64 v[8:9], 13, v[144:145]
	v_and_b32_e32 v26, 0x7e0, v26
	v_lshl_add_u64 v[10:11], s[24:25], 0, v[8:9]
	v_lshlrev_b64 v[8:9], 12, v[144:145]
	v_lshlrev_b32_e32 v144, 2, v26
	v_or_b32_e32 v28, v27, v22
	v_lshl_add_u64 v[10:11], v[10:11], 0, v[144:145]
	v_lshlrev_b32_e32 v144, 2, v2
	v_lshl_add_u64 v[10:11], v[10:11], 0, v[144:145]
	v_lshlrev_b32_e32 v144, 13, v28
	v_lshl_add_u64 v[10:11], v[10:11], 0, v[144:145]
	s_movk_i32 s2, 0x4000
	v_add_co_u32_e32 v28, vcc, s2, v10
	s_mov_b32 s2, 0x8000
	s_nop 0
	v_addc_co_u32_e32 v29, vcc, 0, v11, vcc
	flat_load_dword v30, v[10:11]
	flat_load_dword v31, v[28:29]
	v_add_co_u32_e32 v28, vcc, s2, v10
	s_mov_b32 s2, 0xc000
	s_nop 0
	v_addc_co_u32_e32 v29, vcc, 0, v11, vcc
	flat_load_dword v32, v[28:29]
	v_add_co_u32_e32 v28, vcc, s2, v10
	s_mov_b32 s2, 0x10000
	s_nop 0
	v_addc_co_u32_e32 v29, vcc, 0, v11, vcc
	flat_load_dword v33, v[28:29]
	v_add_co_u32_e32 v28, vcc, s2, v10
	s_mov_b32 s2, 0x1c000
	s_nop 0
	v_addc_co_u32_e32 v29, vcc, 0, v11, vcc
	flat_load_dword v34, v[28:29]
	v_add_co_u32_e32 v28, vcc, s3, v10
	v_lshl_add_u64 v[8:9], s[30:31], 0, v[8:9]
	s_nop 0
	v_addc_co_u32_e32 v29, vcc, 0, v11, vcc
	flat_load_dword v35, v[28:29]
	v_add_co_u32_e32 v28, vcc, s89, v10
	v_lshlrev_b32_e32 v144, 1, v27
	s_nop 0
	v_addc_co_u32_e32 v29, vcc, 0, v11, vcc
	flat_load_dword v36, v[28:29]
	v_add_co_u32_e32 v28, vcc, s2, v10
	s_mov_b32 s2, 0x20000
	s_nop 0
	v_addc_co_u32_e32 v29, vcc, 0, v11, vcc
	flat_load_dword v37, v[28:29]
	v_add_co_u32_e32 v28, vcc, s2, v10
	s_mov_b32 s2, 0x24000
	s_nop 0
	v_addc_co_u32_e32 v29, vcc, 0, v11, vcc
	flat_load_dword v38, v[28:29]
	v_add_co_u32_e32 v28, vcc, s2, v10
	s_mov_b32 s2, 0x28000
	s_nop 0
	v_addc_co_u32_e32 v29, vcc, 0, v11, vcc
	flat_load_dword v39, v[28:29]
	v_add_co_u32_e32 v28, vcc, s2, v10
	s_mov_b32 s2, 0x2c000
	s_nop 0
	v_addc_co_u32_e32 v29, vcc, 0, v11, vcc
	flat_load_dword v40, v[28:29]
	v_add_co_u32_e32 v28, vcc, s2, v10
	s_mov_b32 s2, 0x30000
	s_nop 0
	v_addc_co_u32_e32 v29, vcc, 0, v11, vcc
	flat_load_dword v41, v[28:29]
	v_add_co_u32_e32 v28, vcc, s2, v10
	s_mov_b32 s2, 0x34000
	s_nop 0
	v_addc_co_u32_e32 v29, vcc, 0, v11, vcc
	flat_load_dword v42, v[28:29]
	v_add_co_u32_e32 v28, vcc, s2, v10
	s_mov_b32 s2, 0x38000
	s_nop 0
	v_addc_co_u32_e32 v29, vcc, 0, v11, vcc
	flat_load_dword v43, v[28:29]
	v_add_co_u32_e32 v28, vcc, s2, v10
	s_mov_b32 s2, 0x3c000
	s_nop 0
	v_addc_co_u32_e32 v29, vcc, 0, v11, vcc
	flat_load_dword v44, v[28:29]
	v_add_co_u32_e32 v28, vcc, s2, v10
	s_mov_b32 s2, 0x40000
	s_nop 0
	v_addc_co_u32_e32 v29, vcc, 0, v11, vcc
	flat_load_dword v45, v[28:29]
	v_add_co_u32_e32 v28, vcc, s2, v10
	s_mov_b32 s2, 0x44000
	s_nop 0
	v_addc_co_u32_e32 v29, vcc, 0, v11, vcc
	flat_load_dword v46, v[28:29]
	v_add_co_u32_e32 v28, vcc, s2, v10
	s_mov_b32 s2, 0x48000
	s_nop 0
	v_addc_co_u32_e32 v29, vcc, 0, v11, vcc
	flat_load_dword v47, v[28:29]
	v_add_co_u32_e32 v28, vcc, s2, v10
	s_mov_b32 s2, 0x4c000
	s_nop 0
	v_addc_co_u32_e32 v29, vcc, 0, v11, vcc
	flat_load_dword v48, v[28:29]
	v_add_co_u32_e32 v28, vcc, s2, v10
	s_mov_b32 s2, 0x50000
	s_nop 0
	v_addc_co_u32_e32 v29, vcc, 0, v11, vcc
	flat_load_dword v49, v[28:29]
	v_add_co_u32_e32 v28, vcc, s2, v10
	s_mov_b32 s2, 0x54000
	s_nop 0
	v_addc_co_u32_e32 v29, vcc, 0, v11, vcc
	flat_load_dword v50, v[28:29]
	v_add_co_u32_e32 v28, vcc, s2, v10
	s_mov_b32 s2, 0x58000
	s_nop 0
	v_addc_co_u32_e32 v29, vcc, 0, v11, vcc
	flat_load_dword v51, v[28:29]
	v_add_co_u32_e32 v28, vcc, s2, v10
	s_mov_b32 s2, 0x5c000
	s_nop 0
	v_addc_co_u32_e32 v29, vcc, 0, v11, vcc
	flat_load_dword v52, v[28:29]
	v_add_co_u32_e32 v28, vcc, s2, v10
	s_mov_b32 s2, 0x60000
	s_nop 0
	v_addc_co_u32_e32 v29, vcc, 0, v11, vcc
	flat_load_dword v53, v[28:29]
	v_add_co_u32_e32 v28, vcc, s2, v10
	s_mov_b32 s2, 0x64000
	s_nop 0
	v_addc_co_u32_e32 v29, vcc, 0, v11, vcc
	flat_load_dword v54, v[28:29]
	v_add_co_u32_e32 v28, vcc, s2, v10
	s_mov_b32 s2, 0x68000
	s_nop 0
	v_addc_co_u32_e32 v29, vcc, 0, v11, vcc
	flat_load_dword v55, v[28:29]
	v_add_co_u32_e32 v28, vcc, s2, v10
	s_mov_b32 s2, 0x6c000
	s_nop 0
	v_addc_co_u32_e32 v29, vcc, 0, v11, vcc
	flat_load_dword v56, v[28:29]
	v_add_co_u32_e32 v28, vcc, s2, v10
	s_mov_b32 s2, 0x70000
	s_nop 0
	v_addc_co_u32_e32 v29, vcc, 0, v11, vcc
	flat_load_dword v57, v[28:29]
	v_add_co_u32_e32 v28, vcc, s2, v10
	s_mov_b32 s2, 0x74000
	s_nop 0
	v_addc_co_u32_e32 v29, vcc, 0, v11, vcc
	flat_load_dword v58, v[28:29]
	v_add_co_u32_e32 v28, vcc, s2, v10
	s_mov_b32 s2, 0x78000
	s_nop 0
	v_addc_co_u32_e32 v29, vcc, 0, v11, vcc
	flat_load_dword v59, v[28:29]
	v_add_co_u32_e32 v28, vcc, s2, v10
	s_mov_b32 s2, 0x7c000
	s_nop 0
	v_addc_co_u32_e32 v29, vcc, 0, v11, vcc
	v_add_co_u32_e32 v10, vcc, s2, v10
	flat_load_dword v28, v[28:29]
	s_nop 0
	v_addc_co_u32_e32 v11, vcc, 0, v11, vcc
	flat_load_dword v10, v[10:11]
	v_add_u32_e32 v11, 0x400, v12
	s_waitcnt vmcnt(0) lgkmcnt(0)
	ds_write2_b32 v12, v30, v31 offset1:66
	ds_write2_b32 v12, v32, v33 offset0:132 offset1:198
	ds_write2_b32 v11, v34, v35 offset0:8 offset1:74
	ds_write2_b32 v11, v36, v37 offset0:140 offset1:206
	v_add_u32_e32 v11, 0x800, v12
	ds_write2_b32 v11, v38, v39 offset0:16 offset1:82
	ds_write2_b32 v11, v40, v41 offset0:148 offset1:214
	v_add_u32_e32 v11, 0xc00, v12
	ds_write2_b32 v11, v42, v43 offset0:24 offset1:90
	ds_write2_b32 v11, v44, v45 offset0:156 offset1:222
	v_add_u32_e32 v11, 0x1000, v12
	ds_write2_b32 v11, v46, v47 offset0:32 offset1:98
	ds_write2_b32 v11, v48, v49 offset0:164 offset1:230
	v_add_u32_e32 v11, 0x1400, v12
	ds_write2_b32 v11, v50, v51 offset0:40 offset1:106
	ds_write2_b32 v11, v52, v53 offset0:172 offset1:238
	v_add_u32_e32 v11, 0x1800, v12
	ds_write2_b32 v11, v54, v55 offset0:48 offset1:114
	ds_write2_b32 v11, v56, v57 offset0:180 offset1:246
	v_add_u32_e32 v11, 0x1c00, v12
	ds_write2_b32 v11, v58, v59 offset0:56 offset1:122
	ds_write2_b32 v11, v28, v10 offset0:188 offset1:254
	s_waitcnt lgkmcnt(0)
	ds_read_b32 v10, v13
	ds_read_b32 v11, v13 offset:132
	v_lshl_add_u64 v[8:9], v[8:9], 0, v[144:145]
	v_lshlrev_b32_e32 v144, 1, v0
	v_lshl_add_u64 v[8:9], v[8:9], 0, v[144:145]
	s_waitcnt lgkmcnt(1)
	v_add_u32_e32 v10, 0x8000, v10
	s_waitcnt lgkmcnt(0)
	v_add_u32_e32 v11, 0x8000, v11
	v_perm_b32 v28, v11, v10, s81
	ds_read_b32 v10, v13 offset:264
	ds_read_b32 v11, v13 offset:396
	s_waitcnt lgkmcnt(1)
	v_add_u32_e32 v10, 0x8000, v10
	s_waitcnt lgkmcnt(0)
	v_add_u32_e32 v11, 0x8000, v11
	v_perm_b32 v29, v11, v10, s81
	ds_read_b32 v10, v13 offset:528
	ds_read_b32 v11, v13 offset:660
	s_waitcnt lgkmcnt(1)
	v_add_u32_e32 v10, 0x8000, v10
	s_waitcnt lgkmcnt(0)
	v_add_u32_e32 v11, 0x8000, v11
	v_perm_b32 v30, v11, v10, s81
	ds_read_b32 v10, v13 offset:792
	ds_read_b32 v11, v13 offset:924
	s_waitcnt lgkmcnt(1)
	v_add_u32_e32 v10, 0x8000, v10
	s_waitcnt lgkmcnt(0)
	v_add_u32_e32 v11, 0x8000, v11
	v_perm_b32 v31, v11, v10, s81
	v_or_b32_e32 v10, v26, v17
	v_lshlrev_b32_e32 v144, 12, v10
	v_lshl_add_u64 v[10:11], v[8:9], 0, v[144:145]
	flat_store_dwordx4 v[10:11], v[28:31]
	ds_read_b32 v10, v13 offset:32
	ds_read_b32 v11, v13 offset:164
	s_waitcnt lgkmcnt(0)
	v_add_u32_e32 v10, 0x8000, v10
	v_add_u32_e32 v11, 0x8000, v11
	v_perm_b32 v28, v11, v10, s81
	ds_read_b32 v10, v13 offset:296
	ds_read_b32 v11, v13 offset:428
	s_waitcnt lgkmcnt(0)
	v_add_u32_e32 v10, 0x8000, v10
	v_add_u32_e32 v11, 0x8000, v11
	v_perm_b32 v29, v11, v10, s81
	ds_read_b32 v10, v13 offset:560
	ds_read_b32 v11, v13 offset:692
	s_waitcnt lgkmcnt(0)
	v_add_u32_e32 v10, 0x8000, v10
	v_add_u32_e32 v11, 0x8000, v11
	v_perm_b32 v30, v11, v10, s81
	ds_read_b32 v10, v13 offset:824
	ds_read_b32 v11, v13 offset:956
	s_waitcnt lgkmcnt(0)
	v_add_u32_e32 v10, 0x8000, v10
	v_add_u32_e32 v11, 0x8000, v11
	v_perm_b32 v31, v11, v10, s81
	v_or_b32_e32 v10, v26, v18
	v_lshlrev_b32_e32 v144, 12, v10
	v_lshl_add_u64 v[10:11], v[8:9], 0, v[144:145]
	flat_store_dwordx4 v[10:11], v[28:31]
	ds_read_b32 v10, v13 offset:64
	ds_read_b32 v11, v13 offset:196
	s_waitcnt lgkmcnt(0)
	v_add_u32_e32 v10, 0x8000, v10
	v_add_u32_e32 v11, 0x8000, v11
	v_perm_b32 v28, v11, v10, s81
	ds_read_b32 v10, v13 offset:328
	ds_read_b32 v11, v13 offset:460
	s_waitcnt lgkmcnt(0)
	v_add_u32_e32 v10, 0x8000, v10
	v_add_u32_e32 v11, 0x8000, v11
	v_perm_b32 v29, v11, v10, s81
	ds_read_b32 v10, v13 offset:592
	ds_read_b32 v11, v13 offset:724
	s_waitcnt lgkmcnt(0)
	v_add_u32_e32 v10, 0x8000, v10
	v_add_u32_e32 v11, 0x8000, v11
	v_perm_b32 v30, v11, v10, s81
	ds_read_b32 v10, v13 offset:856
	ds_read_b32 v11, v13 offset:988
	s_waitcnt lgkmcnt(0)
	v_add_u32_e32 v10, 0x8000, v10
	v_add_u32_e32 v11, 0x8000, v11
	v_perm_b32 v31, v11, v10, s81
	v_or_b32_e32 v10, v26, v24
	v_lshlrev_b32_e32 v144, 12, v10
	v_lshl_add_u64 v[10:11], v[8:9], 0, v[144:145]
	flat_store_dwordx4 v[10:11], v[28:31]
	ds_read_b32 v10, v13 offset:96
	ds_read_b32 v11, v13 offset:228
	s_waitcnt lgkmcnt(0)
	v_add_u32_e32 v10, 0x8000, v10
	v_add_u32_e32 v11, 0x8000, v11
	v_perm_b32 v28, v11, v10, s81
	ds_read_b32 v10, v13 offset:360
	ds_read_b32 v11, v13 offset:492
	s_waitcnt lgkmcnt(0)
	v_add_u32_e32 v10, 0x8000, v10
	v_add_u32_e32 v11, 0x8000, v11
	v_perm_b32 v29, v11, v10, s81
	ds_read_b32 v10, v13 offset:624
	ds_read_b32 v11, v13 offset:756
	s_waitcnt lgkmcnt(0)
	v_add_u32_e32 v10, 0x8000, v10
	v_add_u32_e32 v11, 0x8000, v11
	v_perm_b32 v30, v11, v10, s81
	ds_read_b32 v10, v13 offset:888
	ds_read_b32 v11, v13 offset:1020
	s_waitcnt lgkmcnt(0)
	v_add_u32_e32 v10, 0x8000, v10
	v_add_u32_e32 v11, 0x8000, v11
	v_perm_b32 v31, v11, v10, s81
	v_or_b32_e32 v10, v26, v23
	v_lshlrev_b32_e32 v144, 12, v10
	v_lshl_add_u64 v[8:9], v[8:9], 0, v[144:145]
	flat_store_dwordx4 v[8:9], v[28:31]
	s_waitcnt lgkmcnt(0)
